# GU epilogue: two-stage software pipeline interleaving exp/rcp with packed multiplies of the neighbouring block (same instructions, reordered)
# speedup vs baseline: 1.0088x; 1.0088x over previous
; __device__ __forceinline__ unsigned pk2(float lo, float hi) { f32x2_t v = {lo, hi}; bf16x2_t b = __builtin_convertvector(v, bf16x2_t); return __builtin_bit_cast(unsigned, b); }
; __device__ __forceinline__ float sigm(float x) { return frcp(1.f + fexp2(-LOG2E * x)); }
;   __device__ __forceinline__ void operator()(const pg8::f32x4 (&acc)[2][2][4][2], const pg8::Unit& u, int wr, int wc, int fr, int fq) const {
;     ...
;       for (int m = 0; m < 4; ++m) { float v = rs[m]; v += __shfl_xor(v, 16); v += __shfl_xor(v, 32); rs[m] = rsqrtf(v * (1.f / 1024.f) + EPS); }
; #pragma unroll
;       for (int m = 0; m < 4; ++m) {
;         const float r = rs[m]; float v[8];
; #pragma unroll
;         for (int n = 0; n < 2; ++n)
; #pragma unroll
;           for (int c = 0; c < 4; ++c) { const float g = acc[ai][0][m][n][c] * r, uu = acc[ai][1][m][n][c] * r; v[4 * n + c] = g * sigm(g) * uu; }
;         u32x4 w; w.x = pk2(v[0], v[1]); w.y = pk2(v[2], v[3]); w.z = pk2(v[4], v[5]); w.w = pk2(v[6], v[7]);
;         *(u32x4*)(hbuf + (unsigned)(row0 + ai * 128 + m * 16) * DFF + col0) = w;
.Lgu_181_havew:
	v_lshl_add_u64 v[242:243], v[240:241], 0, s[100:101]
	s_mov_b32 s100, 0x16000
	v_rsq_f32_e32 v188, v172
	v_rsq_f32_e32 v190, v174
	v_rsq_f32_e32 v192, v176
	v_rsq_f32_e32 v194, v178
	v_rsq_f32_e32 v196, v180
	v_rsq_f32_e32 v198, v182
	v_rsq_f32_e32 v200, v184
	v_rsq_f32_e32 v202, v186
	v_mul_f32_e32 v188, 0xbfb8aa3b, v188
	v_mul_f32_e32 v190, 0xbfb8aa3b, v190
	v_mul_f32_e32 v192, 0xbfb8aa3b, v192
	v_mul_f32_e32 v194, 0xbfb8aa3b, v194
	v_mul_f32_e32 v196, 0xbfb8aa3b, v196
	v_mul_f32_e32 v198, 0xbfb8aa3b, v198
	v_mul_f32_e32 v200, 0xbfb8aa3b, v200
	v_mul_f32_e32 v202, 0xbfb8aa3b, v202
	v_pk_mul_f32 v[228:229], v[124:125], v[188:189] op_sel_hi:[1,0]
	v_pk_mul_f32 v[230:231], v[126:127], v[188:189] op_sel_hi:[1,0]
	v_pk_mul_f32 v[232:233], v[116:117], v[188:189] op_sel_hi:[1,0]
	v_pk_mul_f32 v[234:235], v[118:119], v[188:189] op_sel_hi:[1,0]
	v_exp_f32_e32 v228, v228
	v_exp_f32_e32 v229, v229
	v_pk_mul_f32 v[124:125], v[124:125], v[120:121]
	v_exp_f32_e32 v230, v230
	v_exp_f32_e32 v231, v231
	v_pk_mul_f32 v[126:127], v[126:127], v[122:123]
	v_exp_f32_e32 v232, v232
	v_exp_f32_e32 v233, v233
	v_pk_mul_f32 v[116:117], v[116:117], v[112:113]
	v_exp_f32_e32 v234, v234
	v_exp_f32_e32 v235, v235
	v_pk_mul_f32 v[118:119], v[118:119], v[114:115]
	v_pk_fma_f32 v[228:229], v[228:229], v[172:173], v[172:173] op_sel_hi:[1,0,0]
	v_pk_fma_f32 v[230:231], v[230:231], v[172:173], v[172:173] op_sel_hi:[1,0,0]
	v_pk_fma_f32 v[232:233], v[232:233], v[172:173], v[172:173] op_sel_hi:[1,0,0]
	v_pk_fma_f32 v[234:235], v[234:235], v[172:173], v[172:173] op_sel_hi:[1,0,0]
	v_rcp_f32_e32 v228, v228
	v_pk_mul_f32 v[204:205], v[108:109], v[190:191] op_sel_hi:[1,0]
	v_rcp_f32_e32 v229, v229
	v_pk_mul_f32 v[206:207], v[110:111], v[190:191] op_sel_hi:[1,0]
	v_rcp_f32_e32 v230, v230
	v_pk_mul_f32 v[208:209], v[104:105], v[190:191] op_sel_hi:[1,0]
	v_rcp_f32_e32 v231, v231
	v_pk_mul_f32 v[210:211], v[106:107], v[190:191] op_sel_hi:[1,0]
	v_rcp_f32_e32 v232, v232
	v_pk_mul_f32 v[108:109], v[108:109], v[100:101]
	v_rcp_f32_e32 v233, v233
	v_pk_mul_f32 v[110:111], v[110:111], v[102:103]
	v_rcp_f32_e32 v234, v234
	v_pk_mul_f32 v[104:105], v[104:105], v[96:97]
	v_rcp_f32_e32 v235, v235
	v_pk_mul_f32 v[106:107], v[106:107], v[98:99]
	v_exp_f32_e32 v204, v204
	v_pk_mul_f32 v[124:125], v[124:125], v[228:229]
	v_exp_f32_e32 v205, v205
	v_pk_mul_f32 v[126:127], v[126:127], v[230:231]
	v_exp_f32_e32 v206, v206
	v_pk_mul_f32 v[116:117], v[116:117], v[232:233]
	v_exp_f32_e32 v207, v207
	v_pk_mul_f32 v[118:119], v[118:119], v[234:235]
	v_exp_f32_e32 v208, v208
	v_cvt_pk_bf16_f32 v236, v124, v125
	v_exp_f32_e32 v209, v209
	v_cvt_pk_bf16_f32 v237, v126, v127
	v_exp_f32_e32 v210, v210
	v_cvt_pk_bf16_f32 v238, v116, v117
	v_exp_f32_e32 v211, v211
	v_cvt_pk_bf16_f32 v239, v118, v119
	s_nop 0
	global_store_dwordx4 v[240:241], v[236:239], off
	v_lshl_add_u64 v[240:241], v[240:241], 0, s[100:101]
	v_pk_fma_f32 v[204:205], v[204:205], v[174:175], v[174:175] op_sel_hi:[1,0,0]
	v_pk_fma_f32 v[206:207], v[206:207], v[174:175], v[174:175] op_sel_hi:[1,0,0]
	v_pk_fma_f32 v[208:209], v[208:209], v[174:175], v[174:175] op_sel_hi:[1,0,0]
	v_pk_fma_f32 v[210:211], v[210:211], v[174:175], v[174:175] op_sel_hi:[1,0,0]
	v_rcp_f32_e32 v204, v204
	v_pk_mul_f32 v[228:229], v[92:93], v[192:193] op_sel_hi:[1,0]
	v_rcp_f32_e32 v205, v205
	v_pk_mul_f32 v[230:231], v[94:95], v[192:193] op_sel_hi:[1,0]
	v_rcp_f32_e32 v206, v206
	v_pk_mul_f32 v[232:233], v[88:89], v[192:193] op_sel_hi:[1,0]
	v_rcp_f32_e32 v207, v207
	v_pk_mul_f32 v[234:235], v[90:91], v[192:193] op_sel_hi:[1,0]
	v_rcp_f32_e32 v208, v208
	v_pk_mul_f32 v[92:93], v[92:93], v[84:85]
	v_rcp_f32_e32 v209, v209
	v_pk_mul_f32 v[94:95], v[94:95], v[86:87]
	v_rcp_f32_e32 v210, v210
	v_pk_mul_f32 v[88:89], v[88:89], v[80:81]
	v_rcp_f32_e32 v211, v211
	v_pk_mul_f32 v[90:91], v[90:91], v[82:83]
	v_exp_f32_e32 v228, v228
	v_pk_mul_f32 v[108:109], v[108:109], v[204:205]
	v_exp_f32_e32 v229, v229
	v_pk_mul_f32 v[110:111], v[110:111], v[206:207]
	v_exp_f32_e32 v230, v230
	v_pk_mul_f32 v[104:105], v[104:105], v[208:209]
	v_exp_f32_e32 v231, v231
	v_pk_mul_f32 v[106:107], v[106:107], v[210:211]
	v_exp_f32_e32 v232, v232
	v_cvt_pk_bf16_f32 v236, v108, v109
	v_exp_f32_e32 v233, v233
	v_cvt_pk_bf16_f32 v237, v110, v111
	v_exp_f32_e32 v234, v234
	v_cvt_pk_bf16_f32 v238, v104, v105
	v_exp_f32_e32 v235, v235
	v_cvt_pk_bf16_f32 v239, v106, v107
	s_nop 0
	global_store_dwordx4 v[240:241], v[236:239], off
	v_lshl_add_u64 v[240:241], v[240:241], 0, s[100:101]
	v_pk_fma_f32 v[228:229], v[228:229], v[176:177], v[176:177] op_sel_hi:[1,0,0]
	v_pk_fma_f32 v[230:231], v[230:231], v[176:177], v[176:177] op_sel_hi:[1,0,0]
	v_pk_fma_f32 v[232:233], v[232:233], v[176:177], v[176:177] op_sel_hi:[1,0,0]
	v_pk_fma_f32 v[234:235], v[234:235], v[176:177], v[176:177] op_sel_hi:[1,0,0]
	v_rcp_f32_e32 v228, v228
	v_pk_mul_f32 v[204:205], v[76:77], v[194:195] op_sel_hi:[1,0]
	v_rcp_f32_e32 v229, v229
	v_pk_mul_f32 v[206:207], v[78:79], v[194:195] op_sel_hi:[1,0]
	v_rcp_f32_e32 v230, v230
	v_pk_mul_f32 v[208:209], v[72:73], v[194:195] op_sel_hi:[1,0]
	v_rcp_f32_e32 v231, v231
	v_pk_mul_f32 v[210:211], v[74:75], v[194:195] op_sel_hi:[1,0]
	v_rcp_f32_e32 v232, v232
	v_pk_mul_f32 v[76:77], v[76:77], v[68:69]
	v_rcp_f32_e32 v233, v233
	v_pk_mul_f32 v[78:79], v[78:79], v[70:71]
	v_rcp_f32_e32 v234, v234
	v_pk_mul_f32 v[72:73], v[72:73], v[64:65]
	v_rcp_f32_e32 v235, v235
	v_pk_mul_f32 v[74:75], v[74:75], v[66:67]
	v_exp_f32_e32 v204, v204
	v_pk_mul_f32 v[92:93], v[92:93], v[228:229]
	v_exp_f32_e32 v205, v205
	v_pk_mul_f32 v[94:95], v[94:95], v[230:231]
	v_exp_f32_e32 v206, v206
; __device__ __forceinline__ unsigned pk2(float lo, float hi) { f32x2_t v = {lo, hi}; bf16x2_t b = __builtin_convertvector(v, bf16x2_t); return __builtin_bit_cast(unsigned, b); }
; __device__ __forceinline__ float sigm(float x) { return frcp(1.f + fexp2(-LOG2E * x)); }
;   __device__ __forceinline__ void operator()(const pg8::f32x4 (&acc)[2][2][4][2], const pg8::Unit& u, int wr, int wc, int fr, int fq) const {
;     ...
;       for (int m = 0; m < 4; ++m) { float v = rs[m]; v += __shfl_xor(v, 16); v += __shfl_xor(v, 32); rs[m] = rsqrtf(v * (1.f / 1024.f) + EPS); }
; #pragma unroll
;       for (int m = 0; m < 4; ++m) {
;         const float r = rs[m]; float v[8];
; #pragma unroll
;         for (int n = 0; n < 2; ++n)
; #pragma unroll
;           for (int c = 0; c < 4; ++c) { const float g = acc[ai][0][m][n][c] * r, uu = acc[ai][1][m][n][c] * r; v[4 * n + c] = g * sigm(g) * uu; }
;         u32x4 w; w.x = pk2(v[0], v[1]); w.y = pk2(v[2], v[3]); w.z = pk2(v[4], v[5]); w.w = pk2(v[6], v[7]);
;         *(u32x4*)(hbuf + (unsigned)(row0 + ai * 128 + m * 16) * DFF + col0) = w;
	v_pk_mul_f32 v[88:89], v[88:89], v[232:233]
	v_exp_f32_e32 v207, v207
	v_pk_mul_f32 v[90:91], v[90:91], v[234:235]
	v_exp_f32_e32 v208, v208
	v_cvt_pk_bf16_f32 v236, v92, v93
	v_exp_f32_e32 v209, v209
	v_cvt_pk_bf16_f32 v237, v94, v95
	v_exp_f32_e32 v210, v210
	v_cvt_pk_bf16_f32 v238, v88, v89
	v_exp_f32_e32 v211, v211
	v_cvt_pk_bf16_f32 v239, v90, v91
	s_nop 0
	global_store_dwordx4 v[240:241], v[236:239], off
	v_lshl_add_u64 v[240:241], v[240:241], 0, s[100:101]
	v_pk_fma_f32 v[204:205], v[204:205], v[178:179], v[178:179] op_sel_hi:[1,0,0]
	v_pk_fma_f32 v[206:207], v[206:207], v[178:179], v[178:179] op_sel_hi:[1,0,0]
	v_pk_fma_f32 v[208:209], v[208:209], v[178:179], v[178:179] op_sel_hi:[1,0,0]
	v_pk_fma_f32 v[210:211], v[210:211], v[178:179], v[178:179] op_sel_hi:[1,0,0]
	v_rcp_f32_e32 v204, v204
	v_pk_mul_f32 v[228:229], v[60:61], v[196:197] op_sel_hi:[1,0]
	v_rcp_f32_e32 v205, v205
	v_pk_mul_f32 v[230:231], v[62:63], v[196:197] op_sel_hi:[1,0]
	v_rcp_f32_e32 v206, v206
	v_pk_mul_f32 v[232:233], v[56:57], v[196:197] op_sel_hi:[1,0]
	v_rcp_f32_e32 v207, v207
	v_pk_mul_f32 v[234:235], v[58:59], v[196:197] op_sel_hi:[1,0]
	v_rcp_f32_e32 v208, v208
	v_pk_mul_f32 v[60:61], v[60:61], v[52:53]
	v_rcp_f32_e32 v209, v209
	v_pk_mul_f32 v[62:63], v[62:63], v[54:55]
	v_rcp_f32_e32 v210, v210
	v_pk_mul_f32 v[56:57], v[56:57], v[48:49]
	v_rcp_f32_e32 v211, v211
	v_pk_mul_f32 v[58:59], v[58:59], v[50:51]
	v_exp_f32_e32 v228, v228
	v_pk_mul_f32 v[76:77], v[76:77], v[204:205]
	v_exp_f32_e32 v229, v229
	v_pk_mul_f32 v[78:79], v[78:79], v[206:207]
	v_exp_f32_e32 v230, v230
	v_pk_mul_f32 v[72:73], v[72:73], v[208:209]
	v_exp_f32_e32 v231, v231
	v_pk_mul_f32 v[74:75], v[74:75], v[210:211]
	v_exp_f32_e32 v232, v232
	v_cvt_pk_bf16_f32 v236, v76, v77
	v_exp_f32_e32 v233, v233
	v_cvt_pk_bf16_f32 v237, v78, v79
	v_exp_f32_e32 v234, v234
	v_cvt_pk_bf16_f32 v238, v72, v73
	v_exp_f32_e32 v235, v235
	v_cvt_pk_bf16_f32 v239, v74, v75
	s_nop 0
	global_store_dwordx4 v[240:241], v[236:239], off
	v_pk_fma_f32 v[228:229], v[228:229], v[180:181], v[180:181] op_sel_hi:[1,0,0]
	v_pk_fma_f32 v[230:231], v[230:231], v[180:181], v[180:181] op_sel_hi:[1,0,0]
	v_pk_fma_f32 v[232:233], v[232:233], v[180:181], v[180:181] op_sel_hi:[1,0,0]
	v_pk_fma_f32 v[234:235], v[234:235], v[180:181], v[180:181] op_sel_hi:[1,0,0]
	v_rcp_f32_e32 v228, v228
	v_pk_mul_f32 v[204:205], v[44:45], v[198:199] op_sel_hi:[1,0]
	v_rcp_f32_e32 v229, v229
	v_pk_mul_f32 v[206:207], v[46:47], v[198:199] op_sel_hi:[1,0]
	v_rcp_f32_e32 v230, v230
	v_pk_mul_f32 v[208:209], v[40:41], v[198:199] op_sel_hi:[1,0]
	v_rcp_f32_e32 v231, v231
	v_pk_mul_f32 v[210:211], v[42:43], v[198:199] op_sel_hi:[1,0]
	v_rcp_f32_e32 v232, v232
	v_pk_mul_f32 v[44:45], v[44:45], v[36:37]
	v_rcp_f32_e32 v233, v233
	v_pk_mul_f32 v[46:47], v[46:47], v[38:39]
	v_rcp_f32_e32 v234, v234
	v_pk_mul_f32 v[40:41], v[40:41], v[32:33]
	v_rcp_f32_e32 v235, v235
	v_pk_mul_f32 v[42:43], v[42:43], v[34:35]
	v_exp_f32_e32 v204, v204
	v_pk_mul_f32 v[60:61], v[60:61], v[228:229]
	v_exp_f32_e32 v205, v205
	v_pk_mul_f32 v[62:63], v[62:63], v[230:231]
	v_exp_f32_e32 v206, v206
	v_pk_mul_f32 v[56:57], v[56:57], v[232:233]
	v_exp_f32_e32 v207, v207
	v_pk_mul_f32 v[58:59], v[58:59], v[234:235]
	v_exp_f32_e32 v208, v208
	v_cvt_pk_bf16_f32 v236, v60, v61
	v_exp_f32_e32 v209, v209
	v_cvt_pk_bf16_f32 v237, v62, v63
	v_exp_f32_e32 v210, v210
	v_cvt_pk_bf16_f32 v238, v56, v57
	v_exp_f32_e32 v211, v211
	v_cvt_pk_bf16_f32 v239, v58, v59
	s_nop 0
	global_store_dwordx4 v[242:243], v[236:239], off
	v_lshl_add_u64 v[242:243], v[242:243], 0, s[100:101]
	v_pk_fma_f32 v[204:205], v[204:205], v[182:183], v[182:183] op_sel_hi:[1,0,0]
	v_pk_fma_f32 v[206:207], v[206:207], v[182:183], v[182:183] op_sel_hi:[1,0,0]
	v_pk_fma_f32 v[208:209], v[208:209], v[182:183], v[182:183] op_sel_hi:[1,0,0]
	v_pk_fma_f32 v[210:211], v[210:211], v[182:183], v[182:183] op_sel_hi:[1,0,0]
; __device__ __forceinline__ unsigned pk2(float lo, float hi) { f32x2_t v = {lo, hi}; bf16x2_t b = __builtin_convertvector(v, bf16x2_t); return __builtin_bit_cast(unsigned, b); }
; __device__ __forceinline__ float sigm(float x) { return frcp(1.f + fexp2(-LOG2E * x)); }
; #define PG8_BAR __builtin_amdgcn_s_barrier()
; template <class Epi, class Sched, bool ALIGN_EPI = false, bool SP2 = false, bool F16 = false, bool TOKPERM = false>
; __device__ __forceinline__ void gemm_phase(PG8_LAS unsigned char* lds, const Gemm g, const Sched& S, const Epi& E, int wv) {
;     ...
;         if (!has_next) break;
; #pragma unroll
;         for (int a = 0; a < 2; ++a)
; #pragma unroll
;             for (int b = 0; b < 2; ++b)
; #pragma unroll
;                 for (int m = 0; m < 4; ++m)
; #pragma unroll
;                     for (int n = 0; n < 2; ++n) acc[a][b][m][n] = (f32x4){0.f, 0.f, 0.f, 0.f};
;         cur = nxt; cA = nA; cB = nB; ++ui;
;         if constexpr (ALIGN_EPI) { if (wr == 1) PG8_BAR; }
;   __device__ __forceinline__ void operator()(const pg8::f32x4 (&acc)[2][2][4][2], const pg8::Unit& u, int wr, int wc, int fr, int fq) const {
;     ...
;       for (int m = 0; m < 4; ++m) {
;         const float r = rs[m]; float v[8];
; #pragma unroll
;         for (int n = 0; n < 2; ++n)
; #pragma unroll
;           for (int c = 0; c < 4; ++c) { const float g = acc[ai][0][m][n][c] * r, uu = acc[ai][1][m][n][c] * r; v[4 * n + c] = g * sigm(g) * uu; }
;         u32x4 w; w.x = pk2(v[0], v[1]); w.y = pk2(v[2], v[3]); w.z = pk2(v[4], v[5]); w.w = pk2(v[6], v[7]);
;         *(u32x4*)(hbuf + (unsigned)(row0 + ai * 128 + m * 16) * DFF + col0) = w;
	v_rcp_f32_e32 v204, v204
	v_pk_mul_f32 v[228:229], v[28:29], v[200:201] op_sel_hi:[1,0]
	v_rcp_f32_e32 v205, v205
	v_pk_mul_f32 v[230:231], v[30:31], v[200:201] op_sel_hi:[1,0]
	v_rcp_f32_e32 v206, v206
	v_pk_mul_f32 v[232:233], v[24:25], v[200:201] op_sel_hi:[1,0]
	v_rcp_f32_e32 v207, v207
	v_pk_mul_f32 v[234:235], v[26:27], v[200:201] op_sel_hi:[1,0]
	v_rcp_f32_e32 v208, v208
	v_pk_mul_f32 v[28:29], v[28:29], v[20:21]
	v_rcp_f32_e32 v209, v209
	v_pk_mul_f32 v[30:31], v[30:31], v[22:23]
	v_rcp_f32_e32 v210, v210
	v_pk_mul_f32 v[24:25], v[24:25], v[16:17]
	v_rcp_f32_e32 v211, v211
	v_pk_mul_f32 v[26:27], v[26:27], v[18:19]
	v_exp_f32_e32 v228, v228
	v_pk_mul_f32 v[44:45], v[44:45], v[204:205]
	v_exp_f32_e32 v229, v229
	v_pk_mul_f32 v[46:47], v[46:47], v[206:207]
	v_exp_f32_e32 v230, v230
	v_pk_mul_f32 v[40:41], v[40:41], v[208:209]
	v_exp_f32_e32 v231, v231
	v_pk_mul_f32 v[42:43], v[42:43], v[210:211]
	v_exp_f32_e32 v232, v232
	v_cvt_pk_bf16_f32 v236, v44, v45
	v_exp_f32_e32 v233, v233
	v_cvt_pk_bf16_f32 v237, v46, v47
	v_exp_f32_e32 v234, v234
	v_cvt_pk_bf16_f32 v238, v40, v41
	v_exp_f32_e32 v235, v235
	v_cvt_pk_bf16_f32 v239, v42, v43
	s_nop 0
	global_store_dwordx4 v[242:243], v[236:239], off
	v_lshl_add_u64 v[242:243], v[242:243], 0, s[100:101]
	v_pk_fma_f32 v[228:229], v[228:229], v[184:185], v[184:185] op_sel_hi:[1,0,0]
	v_pk_fma_f32 v[230:231], v[230:231], v[184:185], v[184:185] op_sel_hi:[1,0,0]
	v_pk_fma_f32 v[232:233], v[232:233], v[184:185], v[184:185] op_sel_hi:[1,0,0]
	v_pk_fma_f32 v[234:235], v[234:235], v[184:185], v[184:185] op_sel_hi:[1,0,0]
	v_rcp_f32_e32 v228, v228
	v_pk_mul_f32 v[204:205], v[12:13], v[202:203] op_sel_hi:[1,0]
	v_rcp_f32_e32 v229, v229
	v_pk_mul_f32 v[206:207], v[14:15], v[202:203] op_sel_hi:[1,0]
	v_rcp_f32_e32 v230, v230
	v_pk_mul_f32 v[208:209], v[8:9], v[202:203] op_sel_hi:[1,0]
	v_rcp_f32_e32 v231, v231
	v_pk_mul_f32 v[210:211], v[10:11], v[202:203] op_sel_hi:[1,0]
	v_rcp_f32_e32 v232, v232
	v_pk_mul_f32 v[12:13], v[12:13], v[4:5]
	v_rcp_f32_e32 v233, v233
	v_pk_mul_f32 v[14:15], v[14:15], v[6:7]
	v_rcp_f32_e32 v234, v234
	v_pk_mul_f32 v[8:9], v[8:9], v[0:1]
	v_rcp_f32_e32 v235, v235
	v_pk_mul_f32 v[10:11], v[10:11], v[2:3]
	v_exp_f32_e32 v204, v204
	v_pk_mul_f32 v[28:29], v[28:29], v[228:229]
	v_exp_f32_e32 v205, v205
	v_pk_mul_f32 v[30:31], v[30:31], v[230:231]
	v_exp_f32_e32 v206, v206
	v_pk_mul_f32 v[24:25], v[24:25], v[232:233]
	v_exp_f32_e32 v207, v207
	v_pk_mul_f32 v[26:27], v[26:27], v[234:235]
	v_exp_f32_e32 v208, v208
	v_cvt_pk_bf16_f32 v236, v28, v29
	v_exp_f32_e32 v209, v209
	v_cvt_pk_bf16_f32 v237, v30, v31
	v_exp_f32_e32 v210, v210
	v_cvt_pk_bf16_f32 v238, v24, v25
	v_exp_f32_e32 v211, v211
	v_cvt_pk_bf16_f32 v239, v26, v27
	s_nop 0
	global_store_dwordx4 v[242:243], v[236:239], off
	v_lshl_add_u64 v[242:243], v[242:243], 0, s[100:101]
	v_pk_fma_f32 v[204:205], v[204:205], v[186:187], v[186:187] op_sel_hi:[1,0,0]
	v_pk_fma_f32 v[206:207], v[206:207], v[186:187], v[186:187] op_sel_hi:[1,0,0]
	v_pk_fma_f32 v[208:209], v[208:209], v[186:187], v[186:187] op_sel_hi:[1,0,0]
	v_pk_fma_f32 v[210:211], v[210:211], v[186:187], v[186:187] op_sel_hi:[1,0,0]
	v_rcp_f32_e32 v204, v204
	v_rcp_f32_e32 v205, v205
	v_rcp_f32_e32 v206, v206
	v_rcp_f32_e32 v207, v207
	v_rcp_f32_e32 v208, v208
	v_rcp_f32_e32 v209, v209
	v_rcp_f32_e32 v210, v210
	v_rcp_f32_e32 v211, v211
	v_pk_mul_f32 v[12:13], v[12:13], v[204:205]
	v_pk_mul_f32 v[14:15], v[14:15], v[206:207]
	v_pk_mul_f32 v[8:9], v[8:9], v[208:209]
	v_pk_mul_f32 v[10:11], v[10:11], v[210:211]
	v_cvt_pk_bf16_f32 v236, v12, v13
	v_cvt_pk_bf16_f32 v237, v14, v15
	v_cvt_pk_bf16_f32 v238, v8, v9
	v_cvt_pk_bf16_f32 v239, v10, v11
	s_nop 0
	global_store_dwordx4 v[242:243], v[236:239], off
	s_andn2_b64 vcc, exec, s[2:3]
	s_mov_b64 s[2:3], -1
	s_cbranch_vccnz .LBB0_177
	s_andn2_b64 vcc, exec, s[10:11]
	s_cbranch_vccnz .LBB0_176
	s_barrier
	s_branch .LBB0_176

; __device__ __forceinline__ unsigned pk2(float lo, float hi) { f32x2_t v = {lo, hi}; bf16x2_t b = __builtin_convertvector(v, bf16x2_t); return __builtin_bit_cast(unsigned, b); }
; __device__ __forceinline__ float sigm(float x) { return frcp(1.f + fexp2(-LOG2E * x)); }
;   __device__ __forceinline__ void operator()(const pg8::f32x4 (&acc)[2][2][4][2], const pg8::Unit& u, int wr, int wc, int fr, int fq) const {
;     ...
;       for (int m = 0; m < 4; ++m) { float v = rs[m]; v += __shfl_xor(v, 16); v += __shfl_xor(v, 32); rs[m] = rsqrtf(v * (1.f / 1024.f) + EPS); }
; #pragma unroll
;       for (int m = 0; m < 4; ++m) {
;         const float r = rs[m]; float v[8];
; #pragma unroll
;         for (int n = 0; n < 2; ++n)
; #pragma unroll
;           for (int c = 0; c < 4; ++c) { const float g = acc[ai][0][m][n][c] * r, uu = acc[ai][1][m][n][c] * r; v[4 * n + c] = g * sigm(g) * uu; }
;         u32x4 w; w.x = pk2(v[0], v[1]); w.y = pk2(v[2], v[3]); w.z = pk2(v[4], v[5]); w.w = pk2(v[6], v[7]);
;         *(u32x4*)(hbuf + (unsigned)(row0 + ai * 128 + m * 16) * DFF + col0) = w;
.Lgu_768_havew:
	v_lshl_add_u64 v[242:243], v[240:241], 0, s[100:101]
	s_mov_b32 s100, 0x16000
	v_rsq_f32_e32 v188, v172
	v_rsq_f32_e32 v190, v174
	v_rsq_f32_e32 v192, v176
	v_rsq_f32_e32 v194, v178
	v_rsq_f32_e32 v196, v180
	v_rsq_f32_e32 v198, v182
	v_rsq_f32_e32 v200, v184
	v_rsq_f32_e32 v202, v186
	v_mul_f32_e32 v188, 0xbfb8aa3b, v188
	v_mul_f32_e32 v190, 0xbfb8aa3b, v190
	v_mul_f32_e32 v192, 0xbfb8aa3b, v192
	v_mul_f32_e32 v194, 0xbfb8aa3b, v194
	v_mul_f32_e32 v196, 0xbfb8aa3b, v196
	v_mul_f32_e32 v198, 0xbfb8aa3b, v198
	v_mul_f32_e32 v200, 0xbfb8aa3b, v200
	v_mul_f32_e32 v202, 0xbfb8aa3b, v202
	v_pk_mul_f32 v[228:229], v[124:125], v[188:189] op_sel_hi:[1,0]
	v_pk_mul_f32 v[230:231], v[126:127], v[188:189] op_sel_hi:[1,0]
	v_pk_mul_f32 v[232:233], v[116:117], v[188:189] op_sel_hi:[1,0]
	v_pk_mul_f32 v[234:235], v[118:119], v[188:189] op_sel_hi:[1,0]
	v_exp_f32_e32 v228, v228
	v_exp_f32_e32 v229, v229
	v_pk_mul_f32 v[124:125], v[124:125], v[120:121]
	v_exp_f32_e32 v230, v230
	v_exp_f32_e32 v231, v231
	v_pk_mul_f32 v[126:127], v[126:127], v[122:123]
	v_exp_f32_e32 v232, v232
	v_exp_f32_e32 v233, v233
	v_pk_mul_f32 v[116:117], v[116:117], v[112:113]
	v_exp_f32_e32 v234, v234
	v_exp_f32_e32 v235, v235
	v_pk_mul_f32 v[118:119], v[118:119], v[114:115]
	v_pk_fma_f32 v[228:229], v[228:229], v[172:173], v[172:173] op_sel_hi:[1,0,0]
	v_pk_fma_f32 v[230:231], v[230:231], v[172:173], v[172:173] op_sel_hi:[1,0,0]
	v_pk_fma_f32 v[232:233], v[232:233], v[172:173], v[172:173] op_sel_hi:[1,0,0]
	v_pk_fma_f32 v[234:235], v[234:235], v[172:173], v[172:173] op_sel_hi:[1,0,0]
	v_rcp_f32_e32 v228, v228
	v_pk_mul_f32 v[204:205], v[108:109], v[190:191] op_sel_hi:[1,0]
	v_rcp_f32_e32 v229, v229
	v_pk_mul_f32 v[206:207], v[110:111], v[190:191] op_sel_hi:[1,0]
	v_rcp_f32_e32 v230, v230
	v_pk_mul_f32 v[208:209], v[104:105], v[190:191] op_sel_hi:[1,0]
	v_rcp_f32_e32 v231, v231
	v_pk_mul_f32 v[210:211], v[106:107], v[190:191] op_sel_hi:[1,0]
	v_rcp_f32_e32 v232, v232
	v_pk_mul_f32 v[108:109], v[108:109], v[100:101]
	v_rcp_f32_e32 v233, v233
	v_pk_mul_f32 v[110:111], v[110:111], v[102:103]
	v_rcp_f32_e32 v234, v234
	v_pk_mul_f32 v[104:105], v[104:105], v[96:97]
	v_rcp_f32_e32 v235, v235
	v_pk_mul_f32 v[106:107], v[106:107], v[98:99]
	v_exp_f32_e32 v204, v204
	v_pk_mul_f32 v[124:125], v[124:125], v[228:229]
	v_exp_f32_e32 v205, v205
	v_pk_mul_f32 v[126:127], v[126:127], v[230:231]
	v_exp_f32_e32 v206, v206
	v_pk_mul_f32 v[116:117], v[116:117], v[232:233]
	v_exp_f32_e32 v207, v207
	v_pk_mul_f32 v[118:119], v[118:119], v[234:235]
	v_exp_f32_e32 v208, v208
	v_cvt_pk_bf16_f32 v236, v124, v125
	v_exp_f32_e32 v209, v209
	v_cvt_pk_bf16_f32 v237, v126, v127
	v_exp_f32_e32 v210, v210
	v_cvt_pk_bf16_f32 v238, v116, v117
	v_exp_f32_e32 v211, v211
	v_cvt_pk_bf16_f32 v239, v118, v119
	s_nop 0
	global_store_dwordx4 v[240:241], v[236:239], off
	v_lshl_add_u64 v[240:241], v[240:241], 0, s[100:101]
	v_pk_fma_f32 v[204:205], v[204:205], v[174:175], v[174:175] op_sel_hi:[1,0,0]
	v_pk_fma_f32 v[206:207], v[206:207], v[174:175], v[174:175] op_sel_hi:[1,0,0]
	v_pk_fma_f32 v[208:209], v[208:209], v[174:175], v[174:175] op_sel_hi:[1,0,0]
	v_pk_fma_f32 v[210:211], v[210:211], v[174:175], v[174:175] op_sel_hi:[1,0,0]
	v_rcp_f32_e32 v204, v204
	v_pk_mul_f32 v[228:229], v[92:93], v[192:193] op_sel_hi:[1,0]
	v_rcp_f32_e32 v205, v205
	v_pk_mul_f32 v[230:231], v[94:95], v[192:193] op_sel_hi:[1,0]
	v_rcp_f32_e32 v206, v206
	v_pk_mul_f32 v[232:233], v[88:89], v[192:193] op_sel_hi:[1,0]
	v_rcp_f32_e32 v207, v207
	v_pk_mul_f32 v[234:235], v[90:91], v[192:193] op_sel_hi:[1,0]
	v_rcp_f32_e32 v208, v208
	v_pk_mul_f32 v[92:93], v[92:93], v[84:85]
	v_rcp_f32_e32 v209, v209
	v_pk_mul_f32 v[94:95], v[94:95], v[86:87]
	v_rcp_f32_e32 v210, v210
	v_pk_mul_f32 v[88:89], v[88:89], v[80:81]
	v_rcp_f32_e32 v211, v211
	v_pk_mul_f32 v[90:91], v[90:91], v[82:83]
	v_exp_f32_e32 v228, v228
	v_pk_mul_f32 v[108:109], v[108:109], v[204:205]
	v_exp_f32_e32 v229, v229
	v_pk_mul_f32 v[110:111], v[110:111], v[206:207]
	v_exp_f32_e32 v230, v230
	v_pk_mul_f32 v[104:105], v[104:105], v[208:209]
	v_exp_f32_e32 v231, v231
	v_pk_mul_f32 v[106:107], v[106:107], v[210:211]
	v_exp_f32_e32 v232, v232
	v_cvt_pk_bf16_f32 v236, v108, v109
	v_exp_f32_e32 v233, v233
	v_cvt_pk_bf16_f32 v237, v110, v111
	v_exp_f32_e32 v234, v234
	v_cvt_pk_bf16_f32 v238, v104, v105
	v_exp_f32_e32 v235, v235
	v_cvt_pk_bf16_f32 v239, v106, v107
	s_nop 0
	global_store_dwordx4 v[240:241], v[236:239], off
	v_lshl_add_u64 v[240:241], v[240:241], 0, s[100:101]
	v_pk_fma_f32 v[228:229], v[228:229], v[176:177], v[176:177] op_sel_hi:[1,0,0]
	v_pk_fma_f32 v[230:231], v[230:231], v[176:177], v[176:177] op_sel_hi:[1,0,0]
	v_pk_fma_f32 v[232:233], v[232:233], v[176:177], v[176:177] op_sel_hi:[1,0,0]
	v_pk_fma_f32 v[234:235], v[234:235], v[176:177], v[176:177] op_sel_hi:[1,0,0]
	v_rcp_f32_e32 v228, v228
	v_pk_mul_f32 v[204:205], v[76:77], v[194:195] op_sel_hi:[1,0]
	v_rcp_f32_e32 v229, v229
	v_pk_mul_f32 v[206:207], v[78:79], v[194:195] op_sel_hi:[1,0]
	v_rcp_f32_e32 v230, v230
	v_pk_mul_f32 v[208:209], v[72:73], v[194:195] op_sel_hi:[1,0]
	v_rcp_f32_e32 v231, v231
	v_pk_mul_f32 v[210:211], v[74:75], v[194:195] op_sel_hi:[1,0]
	v_rcp_f32_e32 v232, v232
	v_pk_mul_f32 v[76:77], v[76:77], v[68:69]
	v_rcp_f32_e32 v233, v233
	v_pk_mul_f32 v[78:79], v[78:79], v[70:71]
	v_rcp_f32_e32 v234, v234
	v_pk_mul_f32 v[72:73], v[72:73], v[64:65]
	v_rcp_f32_e32 v235, v235
	v_pk_mul_f32 v[74:75], v[74:75], v[66:67]
	v_exp_f32_e32 v204, v204
	v_pk_mul_f32 v[92:93], v[92:93], v[228:229]
	v_exp_f32_e32 v205, v205
	v_pk_mul_f32 v[94:95], v[94:95], v[230:231]
	v_exp_f32_e32 v206, v206
; __device__ __forceinline__ unsigned pk2(float lo, float hi) { f32x2_t v = {lo, hi}; bf16x2_t b = __builtin_convertvector(v, bf16x2_t); return __builtin_bit_cast(unsigned, b); }
; __device__ __forceinline__ float sigm(float x) { return frcp(1.f + fexp2(-LOG2E * x)); }
;   __device__ __forceinline__ void operator()(const pg8::f32x4 (&acc)[2][2][4][2], const pg8::Unit& u, int wr, int wc, int fr, int fq) const {
;     ...
;       for (int m = 0; m < 4; ++m) { float v = rs[m]; v += __shfl_xor(v, 16); v += __shfl_xor(v, 32); rs[m] = rsqrtf(v * (1.f / 1024.f) + EPS); }
; #pragma unroll
;       for (int m = 0; m < 4; ++m) {
;         const float r = rs[m]; float v[8];
; #pragma unroll
;         for (int n = 0; n < 2; ++n)
; #pragma unroll
;           for (int c = 0; c < 4; ++c) { const float g = acc[ai][0][m][n][c] * r, uu = acc[ai][1][m][n][c] * r; v[4 * n + c] = g * sigm(g) * uu; }
;         u32x4 w; w.x = pk2(v[0], v[1]); w.y = pk2(v[2], v[3]); w.z = pk2(v[4], v[5]); w.w = pk2(v[6], v[7]);
;         *(u32x4*)(hbuf + (unsigned)(row0 + ai * 128 + m * 16) * DFF + col0) = w;
	v_pk_mul_f32 v[88:89], v[88:89], v[232:233]
	v_exp_f32_e32 v207, v207
	v_pk_mul_f32 v[90:91], v[90:91], v[234:235]
	v_exp_f32_e32 v208, v208
	v_cvt_pk_bf16_f32 v236, v92, v93
	v_exp_f32_e32 v209, v209
	v_cvt_pk_bf16_f32 v237, v94, v95
	v_exp_f32_e32 v210, v210
	v_cvt_pk_bf16_f32 v238, v88, v89
	v_exp_f32_e32 v211, v211
	v_cvt_pk_bf16_f32 v239, v90, v91
	s_nop 0
	global_store_dwordx4 v[240:241], v[236:239], off
	v_lshl_add_u64 v[240:241], v[240:241], 0, s[100:101]
	v_pk_fma_f32 v[204:205], v[204:205], v[178:179], v[178:179] op_sel_hi:[1,0,0]
	v_pk_fma_f32 v[206:207], v[206:207], v[178:179], v[178:179] op_sel_hi:[1,0,0]
	v_pk_fma_f32 v[208:209], v[208:209], v[178:179], v[178:179] op_sel_hi:[1,0,0]
	v_pk_fma_f32 v[210:211], v[210:211], v[178:179], v[178:179] op_sel_hi:[1,0,0]
	v_rcp_f32_e32 v204, v204
	v_pk_mul_f32 v[228:229], v[60:61], v[196:197] op_sel_hi:[1,0]
	v_rcp_f32_e32 v205, v205
	v_pk_mul_f32 v[230:231], v[62:63], v[196:197] op_sel_hi:[1,0]
	v_rcp_f32_e32 v206, v206
	v_pk_mul_f32 v[232:233], v[56:57], v[196:197] op_sel_hi:[1,0]
	v_rcp_f32_e32 v207, v207
	v_pk_mul_f32 v[234:235], v[58:59], v[196:197] op_sel_hi:[1,0]
	v_rcp_f32_e32 v208, v208
	v_pk_mul_f32 v[60:61], v[60:61], v[52:53]
	v_rcp_f32_e32 v209, v209
	v_pk_mul_f32 v[62:63], v[62:63], v[54:55]
	v_rcp_f32_e32 v210, v210
	v_pk_mul_f32 v[56:57], v[56:57], v[48:49]
	v_rcp_f32_e32 v211, v211
	v_pk_mul_f32 v[58:59], v[58:59], v[50:51]
	v_exp_f32_e32 v228, v228
	v_pk_mul_f32 v[76:77], v[76:77], v[204:205]
	v_exp_f32_e32 v229, v229
	v_pk_mul_f32 v[78:79], v[78:79], v[206:207]
	v_exp_f32_e32 v230, v230
	v_pk_mul_f32 v[72:73], v[72:73], v[208:209]
	v_exp_f32_e32 v231, v231
	v_pk_mul_f32 v[74:75], v[74:75], v[210:211]
	v_exp_f32_e32 v232, v232
	v_cvt_pk_bf16_f32 v236, v76, v77
	v_exp_f32_e32 v233, v233
	v_cvt_pk_bf16_f32 v237, v78, v79
	v_exp_f32_e32 v234, v234
	v_cvt_pk_bf16_f32 v238, v72, v73
	v_exp_f32_e32 v235, v235
	v_cvt_pk_bf16_f32 v239, v74, v75
	s_nop 0
	global_store_dwordx4 v[240:241], v[236:239], off
	v_pk_fma_f32 v[228:229], v[228:229], v[180:181], v[180:181] op_sel_hi:[1,0,0]
	v_pk_fma_f32 v[230:231], v[230:231], v[180:181], v[180:181] op_sel_hi:[1,0,0]
	v_pk_fma_f32 v[232:233], v[232:233], v[180:181], v[180:181] op_sel_hi:[1,0,0]
	v_pk_fma_f32 v[234:235], v[234:235], v[180:181], v[180:181] op_sel_hi:[1,0,0]
	v_rcp_f32_e32 v228, v228
	v_pk_mul_f32 v[204:205], v[44:45], v[198:199] op_sel_hi:[1,0]
	v_rcp_f32_e32 v229, v229
	v_pk_mul_f32 v[206:207], v[46:47], v[198:199] op_sel_hi:[1,0]
	v_rcp_f32_e32 v230, v230
	v_pk_mul_f32 v[208:209], v[40:41], v[198:199] op_sel_hi:[1,0]
	v_rcp_f32_e32 v231, v231
	v_pk_mul_f32 v[210:211], v[42:43], v[198:199] op_sel_hi:[1,0]
	v_rcp_f32_e32 v232, v232
	v_pk_mul_f32 v[44:45], v[44:45], v[36:37]
	v_rcp_f32_e32 v233, v233
	v_pk_mul_f32 v[46:47], v[46:47], v[38:39]
	v_rcp_f32_e32 v234, v234
	v_pk_mul_f32 v[40:41], v[40:41], v[32:33]
	v_rcp_f32_e32 v235, v235
	v_pk_mul_f32 v[42:43], v[42:43], v[34:35]
	v_exp_f32_e32 v204, v204
	v_pk_mul_f32 v[60:61], v[60:61], v[228:229]
	v_exp_f32_e32 v205, v205
	v_pk_mul_f32 v[62:63], v[62:63], v[230:231]
	v_exp_f32_e32 v206, v206
	v_pk_mul_f32 v[56:57], v[56:57], v[232:233]
	v_exp_f32_e32 v207, v207
	v_pk_mul_f32 v[58:59], v[58:59], v[234:235]
	v_exp_f32_e32 v208, v208
	v_cvt_pk_bf16_f32 v236, v60, v61
	v_exp_f32_e32 v209, v209
	v_cvt_pk_bf16_f32 v237, v62, v63
	v_exp_f32_e32 v210, v210
	v_cvt_pk_bf16_f32 v238, v56, v57
	v_exp_f32_e32 v211, v211
	v_cvt_pk_bf16_f32 v239, v58, v59
	s_nop 0
	global_store_dwordx4 v[242:243], v[236:239], off
	v_lshl_add_u64 v[242:243], v[242:243], 0, s[100:101]
	v_pk_fma_f32 v[204:205], v[204:205], v[182:183], v[182:183] op_sel_hi:[1,0,0]
	v_pk_fma_f32 v[206:207], v[206:207], v[182:183], v[182:183] op_sel_hi:[1,0,0]
	v_pk_fma_f32 v[208:209], v[208:209], v[182:183], v[182:183] op_sel_hi:[1,0,0]
	v_pk_fma_f32 v[210:211], v[210:211], v[182:183], v[182:183] op_sel_hi:[1,0,0]
; __device__ __forceinline__ unsigned pk2(float lo, float hi) { f32x2_t v = {lo, hi}; bf16x2_t b = __builtin_convertvector(v, bf16x2_t); return __builtin_bit_cast(unsigned, b); }
; __device__ __forceinline__ float sigm(float x) { return frcp(1.f + fexp2(-LOG2E * x)); }
; #define PG8_BAR __builtin_amdgcn_s_barrier()
; template <class Epi, class Sched, bool ALIGN_EPI = false, bool SP2 = false, bool F16 = false, bool TOKPERM = false>
; __device__ __forceinline__ void gemm_phase(PG8_LAS unsigned char* lds, const Gemm g, const Sched& S, const Epi& E, int wv) {
;     ...
;         if (!has_next) break;
; #pragma unroll
;         for (int a = 0; a < 2; ++a)
; #pragma unroll
;             for (int b = 0; b < 2; ++b)
; #pragma unroll
;                 for (int m = 0; m < 4; ++m)
; #pragma unroll
;                     for (int n = 0; n < 2; ++n) acc[a][b][m][n] = (f32x4){0.f, 0.f, 0.f, 0.f};
;         cur = nxt; cA = nA; cB = nB; ++ui;
;         if constexpr (ALIGN_EPI) { if (wr == 1) PG8_BAR; }
;   __device__ __forceinline__ void operator()(const pg8::f32x4 (&acc)[2][2][4][2], const pg8::Unit& u, int wr, int wc, int fr, int fq) const {
;     ...
;       for (int m = 0; m < 4; ++m) {
;         const float r = rs[m]; float v[8];
; #pragma unroll
;         for (int n = 0; n < 2; ++n)
; #pragma unroll
;           for (int c = 0; c < 4; ++c) { const float g = acc[ai][0][m][n][c] * r, uu = acc[ai][1][m][n][c] * r; v[4 * n + c] = g * sigm(g) * uu; }
;         u32x4 w; w.x = pk2(v[0], v[1]); w.y = pk2(v[2], v[3]); w.z = pk2(v[4], v[5]); w.w = pk2(v[6], v[7]);
;         *(u32x4*)(hbuf + (unsigned)(row0 + ai * 128 + m * 16) * DFF + col0) = w;
	v_rcp_f32_e32 v204, v204
	v_pk_mul_f32 v[228:229], v[28:29], v[200:201] op_sel_hi:[1,0]
	v_rcp_f32_e32 v205, v205
	v_pk_mul_f32 v[230:231], v[30:31], v[200:201] op_sel_hi:[1,0]
	v_rcp_f32_e32 v206, v206
	v_pk_mul_f32 v[232:233], v[24:25], v[200:201] op_sel_hi:[1,0]
	v_rcp_f32_e32 v207, v207
	v_pk_mul_f32 v[234:235], v[26:27], v[200:201] op_sel_hi:[1,0]
	v_rcp_f32_e32 v208, v208
	v_pk_mul_f32 v[28:29], v[28:29], v[20:21]
	v_rcp_f32_e32 v209, v209
	v_pk_mul_f32 v[30:31], v[30:31], v[22:23]
	v_rcp_f32_e32 v210, v210
	v_pk_mul_f32 v[24:25], v[24:25], v[16:17]
	v_rcp_f32_e32 v211, v211
	v_pk_mul_f32 v[26:27], v[26:27], v[18:19]
	v_exp_f32_e32 v228, v228
	v_pk_mul_f32 v[44:45], v[44:45], v[204:205]
	v_exp_f32_e32 v229, v229
	v_pk_mul_f32 v[46:47], v[46:47], v[206:207]
	v_exp_f32_e32 v230, v230
	v_pk_mul_f32 v[40:41], v[40:41], v[208:209]
	v_exp_f32_e32 v231, v231
	v_pk_mul_f32 v[42:43], v[42:43], v[210:211]
	v_exp_f32_e32 v232, v232
	v_cvt_pk_bf16_f32 v236, v44, v45
	v_exp_f32_e32 v233, v233
	v_cvt_pk_bf16_f32 v237, v46, v47
	v_exp_f32_e32 v234, v234
	v_cvt_pk_bf16_f32 v238, v40, v41
	v_exp_f32_e32 v235, v235
	v_cvt_pk_bf16_f32 v239, v42, v43
	s_nop 0
	global_store_dwordx4 v[242:243], v[236:239], off
	v_lshl_add_u64 v[242:243], v[242:243], 0, s[100:101]
	v_pk_fma_f32 v[228:229], v[228:229], v[184:185], v[184:185] op_sel_hi:[1,0,0]
	v_pk_fma_f32 v[230:231], v[230:231], v[184:185], v[184:185] op_sel_hi:[1,0,0]
	v_pk_fma_f32 v[232:233], v[232:233], v[184:185], v[184:185] op_sel_hi:[1,0,0]
	v_pk_fma_f32 v[234:235], v[234:235], v[184:185], v[184:185] op_sel_hi:[1,0,0]
	v_rcp_f32_e32 v228, v228
	v_pk_mul_f32 v[204:205], v[12:13], v[202:203] op_sel_hi:[1,0]
	v_rcp_f32_e32 v229, v229
	v_pk_mul_f32 v[206:207], v[14:15], v[202:203] op_sel_hi:[1,0]
	v_rcp_f32_e32 v230, v230
	v_pk_mul_f32 v[208:209], v[8:9], v[202:203] op_sel_hi:[1,0]
	v_rcp_f32_e32 v231, v231
	v_pk_mul_f32 v[210:211], v[10:11], v[202:203] op_sel_hi:[1,0]
	v_rcp_f32_e32 v232, v232
	v_pk_mul_f32 v[12:13], v[12:13], v[4:5]
	v_rcp_f32_e32 v233, v233
	v_pk_mul_f32 v[14:15], v[14:15], v[6:7]
	v_rcp_f32_e32 v234, v234
	v_pk_mul_f32 v[8:9], v[8:9], v[0:1]
	v_rcp_f32_e32 v235, v235
	v_pk_mul_f32 v[10:11], v[10:11], v[2:3]
	v_exp_f32_e32 v204, v204
	v_pk_mul_f32 v[28:29], v[28:29], v[228:229]
	v_exp_f32_e32 v205, v205
	v_pk_mul_f32 v[30:31], v[30:31], v[230:231]
	v_exp_f32_e32 v206, v206
	v_pk_mul_f32 v[24:25], v[24:25], v[232:233]
	v_exp_f32_e32 v207, v207
	v_pk_mul_f32 v[26:27], v[26:27], v[234:235]
	v_exp_f32_e32 v208, v208
	v_cvt_pk_bf16_f32 v236, v28, v29
	v_exp_f32_e32 v209, v209
	v_cvt_pk_bf16_f32 v237, v30, v31
	v_exp_f32_e32 v210, v210
	v_cvt_pk_bf16_f32 v238, v24, v25
	v_exp_f32_e32 v211, v211
	v_cvt_pk_bf16_f32 v239, v26, v27
	s_nop 0
	global_store_dwordx4 v[242:243], v[236:239], off
	v_lshl_add_u64 v[242:243], v[242:243], 0, s[100:101]
	v_pk_fma_f32 v[204:205], v[204:205], v[186:187], v[186:187] op_sel_hi:[1,0,0]
	v_pk_fma_f32 v[206:207], v[206:207], v[186:187], v[186:187] op_sel_hi:[1,0,0]
	v_pk_fma_f32 v[208:209], v[208:209], v[186:187], v[186:187] op_sel_hi:[1,0,0]
	v_pk_fma_f32 v[210:211], v[210:211], v[186:187], v[186:187] op_sel_hi:[1,0,0]
	v_rcp_f32_e32 v204, v204
	v_rcp_f32_e32 v205, v205
	v_rcp_f32_e32 v206, v206
	v_rcp_f32_e32 v207, v207
	v_rcp_f32_e32 v208, v208
	v_rcp_f32_e32 v209, v209
	v_rcp_f32_e32 v210, v210
	v_rcp_f32_e32 v211, v211
	v_pk_mul_f32 v[12:13], v[12:13], v[204:205]
	v_pk_mul_f32 v[14:15], v[14:15], v[206:207]
	v_pk_mul_f32 v[8:9], v[8:9], v[208:209]
	v_pk_mul_f32 v[10:11], v[10:11], v[210:211]
	v_cvt_pk_bf16_f32 v236, v12, v13
	v_cvt_pk_bf16_f32 v237, v14, v15
	v_cvt_pk_bf16_f32 v238, v8, v9
	v_cvt_pk_bf16_f32 v239, v10, v11
	s_nop 0
	global_store_dwordx4 v[242:243], v[236:239], off
	s_andn2_b64 vcc, exec, s[6:7]
	s_mov_b64 s[6:7], -1
	s_cbranch_vccnz .LBB0_764
	s_andn2_b64 vcc, exec, s[14:15]
	s_cbranch_vccnz .LBB0_763
	s_barrier
	s_branch .LBB0_763

; __device__ __forceinline__ unsigned pk2(float lo, float hi) { f32x2_t v = {lo, hi}; bf16x2_t b = __builtin_convertvector(v, bf16x2_t); return __builtin_bit_cast(unsigned, b); }
; __device__ __forceinline__ float sigm(float x) { return frcp(1.f + fexp2(-LOG2E * x)); }
;   __device__ __forceinline__ void operator()(const pg8::f32x4 (&acc)[2][2][4][2], const pg8::Unit& u, int wr, int wc, int fr, int fq) const {
;     ...
;       for (int m = 0; m < 4; ++m) { float v = rs[m]; v += __shfl_xor(v, 16); v += __shfl_xor(v, 32); rs[m] = rsqrtf(v * (1.f / 1024.f) + EPS); }
; #pragma unroll
;       for (int m = 0; m < 4; ++m) {
;         const float r = rs[m]; float v[8];
; #pragma unroll
;         for (int n = 0; n < 2; ++n)
; #pragma unroll
;           for (int c = 0; c < 4; ++c) { const float g = acc[ai][0][m][n][c] * r, uu = acc[ai][1][m][n][c] * r; v[4 * n + c] = g * sigm(g) * uu; }
;         u32x4 w; w.x = pk2(v[0], v[1]); w.y = pk2(v[2], v[3]); w.z = pk2(v[4], v[5]); w.w = pk2(v[6], v[7]);
;         *(u32x4*)(hbuf + (unsigned)(row0 + ai * 128 + m * 16) * DFF + col0) = w;
.Lgu_1607_havew:
	v_lshl_add_u64 v[242:243], v[240:241], 0, s[100:101]
	s_mov_b32 s100, 0x16000
	v_rsq_f32_e32 v188, v172
	v_rsq_f32_e32 v190, v174
	v_rsq_f32_e32 v192, v176
	v_rsq_f32_e32 v194, v178
	v_rsq_f32_e32 v196, v180
	v_rsq_f32_e32 v198, v182
	v_rsq_f32_e32 v200, v184
	v_rsq_f32_e32 v202, v186
	v_mul_f32_e32 v188, 0xbfb8aa3b, v188
	v_mul_f32_e32 v190, 0xbfb8aa3b, v190
	v_mul_f32_e32 v192, 0xbfb8aa3b, v192
	v_mul_f32_e32 v194, 0xbfb8aa3b, v194
	v_mul_f32_e32 v196, 0xbfb8aa3b, v196
	v_mul_f32_e32 v198, 0xbfb8aa3b, v198
	v_mul_f32_e32 v200, 0xbfb8aa3b, v200
	v_mul_f32_e32 v202, 0xbfb8aa3b, v202
	v_pk_mul_f32 v[228:229], v[124:125], v[188:189] op_sel_hi:[1,0]
	v_pk_mul_f32 v[230:231], v[126:127], v[188:189] op_sel_hi:[1,0]
	v_pk_mul_f32 v[232:233], v[116:117], v[188:189] op_sel_hi:[1,0]
	v_pk_mul_f32 v[234:235], v[118:119], v[188:189] op_sel_hi:[1,0]
	v_exp_f32_e32 v228, v228
	v_exp_f32_e32 v229, v229
	v_pk_mul_f32 v[124:125], v[124:125], v[120:121]
	v_exp_f32_e32 v230, v230
	v_exp_f32_e32 v231, v231
	v_pk_mul_f32 v[126:127], v[126:127], v[122:123]
	v_exp_f32_e32 v232, v232
	v_exp_f32_e32 v233, v233
	v_pk_mul_f32 v[116:117], v[116:117], v[112:113]
	v_exp_f32_e32 v234, v234
	v_exp_f32_e32 v235, v235
	v_pk_mul_f32 v[118:119], v[118:119], v[114:115]
	v_pk_fma_f32 v[228:229], v[228:229], v[172:173], v[172:173] op_sel_hi:[1,0,0]
	v_pk_fma_f32 v[230:231], v[230:231], v[172:173], v[172:173] op_sel_hi:[1,0,0]
	v_pk_fma_f32 v[232:233], v[232:233], v[172:173], v[172:173] op_sel_hi:[1,0,0]
	v_pk_fma_f32 v[234:235], v[234:235], v[172:173], v[172:173] op_sel_hi:[1,0,0]
	v_rcp_f32_e32 v228, v228
	v_pk_mul_f32 v[204:205], v[108:109], v[190:191] op_sel_hi:[1,0]
	v_rcp_f32_e32 v229, v229
	v_pk_mul_f32 v[206:207], v[110:111], v[190:191] op_sel_hi:[1,0]
	v_rcp_f32_e32 v230, v230
	v_pk_mul_f32 v[208:209], v[104:105], v[190:191] op_sel_hi:[1,0]
	v_rcp_f32_e32 v231, v231
	v_pk_mul_f32 v[210:211], v[106:107], v[190:191] op_sel_hi:[1,0]
	v_rcp_f32_e32 v232, v232
	v_pk_mul_f32 v[108:109], v[108:109], v[100:101]
	v_rcp_f32_e32 v233, v233
	v_pk_mul_f32 v[110:111], v[110:111], v[102:103]
	v_rcp_f32_e32 v234, v234
	v_pk_mul_f32 v[104:105], v[104:105], v[96:97]
	v_rcp_f32_e32 v235, v235
	v_pk_mul_f32 v[106:107], v[106:107], v[98:99]
	v_exp_f32_e32 v204, v204
	v_pk_mul_f32 v[124:125], v[124:125], v[228:229]
	v_exp_f32_e32 v205, v205
	v_pk_mul_f32 v[126:127], v[126:127], v[230:231]
	v_exp_f32_e32 v206, v206
	v_pk_mul_f32 v[116:117], v[116:117], v[232:233]
	v_exp_f32_e32 v207, v207
	v_pk_mul_f32 v[118:119], v[118:119], v[234:235]
	v_exp_f32_e32 v208, v208
	v_cvt_pk_bf16_f32 v236, v124, v125
	v_exp_f32_e32 v209, v209
	v_cvt_pk_bf16_f32 v237, v126, v127
	v_exp_f32_e32 v210, v210
	v_cvt_pk_bf16_f32 v238, v116, v117
	v_exp_f32_e32 v211, v211
	v_cvt_pk_bf16_f32 v239, v118, v119
	s_nop 0
	global_store_dwordx4 v[240:241], v[236:239], off
	v_lshl_add_u64 v[240:241], v[240:241], 0, s[100:101]
	v_pk_fma_f32 v[204:205], v[204:205], v[174:175], v[174:175] op_sel_hi:[1,0,0]
	v_pk_fma_f32 v[206:207], v[206:207], v[174:175], v[174:175] op_sel_hi:[1,0,0]
	v_pk_fma_f32 v[208:209], v[208:209], v[174:175], v[174:175] op_sel_hi:[1,0,0]
	v_pk_fma_f32 v[210:211], v[210:211], v[174:175], v[174:175] op_sel_hi:[1,0,0]
	v_rcp_f32_e32 v204, v204
	v_pk_mul_f32 v[228:229], v[92:93], v[192:193] op_sel_hi:[1,0]
	v_rcp_f32_e32 v205, v205
	v_pk_mul_f32 v[230:231], v[94:95], v[192:193] op_sel_hi:[1,0]
	v_rcp_f32_e32 v206, v206
	v_pk_mul_f32 v[232:233], v[88:89], v[192:193] op_sel_hi:[1,0]
	v_rcp_f32_e32 v207, v207
	v_pk_mul_f32 v[234:235], v[90:91], v[192:193] op_sel_hi:[1,0]
	v_rcp_f32_e32 v208, v208
	v_pk_mul_f32 v[92:93], v[92:93], v[84:85]
	v_rcp_f32_e32 v209, v209
	v_pk_mul_f32 v[94:95], v[94:95], v[86:87]
	v_rcp_f32_e32 v210, v210
	v_pk_mul_f32 v[88:89], v[88:89], v[80:81]
	v_rcp_f32_e32 v211, v211
	v_pk_mul_f32 v[90:91], v[90:91], v[82:83]
	v_exp_f32_e32 v228, v228
	v_pk_mul_f32 v[108:109], v[108:109], v[204:205]
	v_exp_f32_e32 v229, v229
	v_pk_mul_f32 v[110:111], v[110:111], v[206:207]
	v_exp_f32_e32 v230, v230
	v_pk_mul_f32 v[104:105], v[104:105], v[208:209]
	v_exp_f32_e32 v231, v231
	v_pk_mul_f32 v[106:107], v[106:107], v[210:211]
	v_exp_f32_e32 v232, v232
	v_cvt_pk_bf16_f32 v236, v108, v109
	v_exp_f32_e32 v233, v233
	v_cvt_pk_bf16_f32 v237, v110, v111
	v_exp_f32_e32 v234, v234
	v_cvt_pk_bf16_f32 v238, v104, v105
	v_exp_f32_e32 v235, v235
	v_cvt_pk_bf16_f32 v239, v106, v107
	s_nop 0
	global_store_dwordx4 v[240:241], v[236:239], off
	v_lshl_add_u64 v[240:241], v[240:241], 0, s[100:101]
	v_pk_fma_f32 v[228:229], v[228:229], v[176:177], v[176:177] op_sel_hi:[1,0,0]
	v_pk_fma_f32 v[230:231], v[230:231], v[176:177], v[176:177] op_sel_hi:[1,0,0]
	v_pk_fma_f32 v[232:233], v[232:233], v[176:177], v[176:177] op_sel_hi:[1,0,0]
	v_pk_fma_f32 v[234:235], v[234:235], v[176:177], v[176:177] op_sel_hi:[1,0,0]
	v_rcp_f32_e32 v228, v228
	v_pk_mul_f32 v[204:205], v[76:77], v[194:195] op_sel_hi:[1,0]
	v_rcp_f32_e32 v229, v229
	v_pk_mul_f32 v[206:207], v[78:79], v[194:195] op_sel_hi:[1,0]
	v_rcp_f32_e32 v230, v230
	v_pk_mul_f32 v[208:209], v[72:73], v[194:195] op_sel_hi:[1,0]
	v_rcp_f32_e32 v231, v231
	v_pk_mul_f32 v[210:211], v[74:75], v[194:195] op_sel_hi:[1,0]
	v_rcp_f32_e32 v232, v232
	v_pk_mul_f32 v[76:77], v[76:77], v[68:69]
	v_rcp_f32_e32 v233, v233
	v_pk_mul_f32 v[78:79], v[78:79], v[70:71]
	v_rcp_f32_e32 v234, v234
	v_pk_mul_f32 v[72:73], v[72:73], v[64:65]
	v_rcp_f32_e32 v235, v235
	v_pk_mul_f32 v[74:75], v[74:75], v[66:67]
	v_exp_f32_e32 v204, v204
	v_pk_mul_f32 v[92:93], v[92:93], v[228:229]
	v_exp_f32_e32 v205, v205
	v_pk_mul_f32 v[94:95], v[94:95], v[230:231]
	v_exp_f32_e32 v206, v206
; __device__ __forceinline__ unsigned pk2(float lo, float hi) { f32x2_t v = {lo, hi}; bf16x2_t b = __builtin_convertvector(v, bf16x2_t); return __builtin_bit_cast(unsigned, b); }
; __device__ __forceinline__ float sigm(float x) { return frcp(1.f + fexp2(-LOG2E * x)); }
;   __device__ __forceinline__ void operator()(const pg8::f32x4 (&acc)[2][2][4][2], const pg8::Unit& u, int wr, int wc, int fr, int fq) const {
;     ...
;       for (int m = 0; m < 4; ++m) { float v = rs[m]; v += __shfl_xor(v, 16); v += __shfl_xor(v, 32); rs[m] = rsqrtf(v * (1.f / 1024.f) + EPS); }
; #pragma unroll
;       for (int m = 0; m < 4; ++m) {
;         const float r = rs[m]; float v[8];
; #pragma unroll
;         for (int n = 0; n < 2; ++n)
; #pragma unroll
;           for (int c = 0; c < 4; ++c) { const float g = acc[ai][0][m][n][c] * r, uu = acc[ai][1][m][n][c] * r; v[4 * n + c] = g * sigm(g) * uu; }
;         u32x4 w; w.x = pk2(v[0], v[1]); w.y = pk2(v[2], v[3]); w.z = pk2(v[4], v[5]); w.w = pk2(v[6], v[7]);
;         *(u32x4*)(hbuf + (unsigned)(row0 + ai * 128 + m * 16) * DFF + col0) = w;
	v_pk_mul_f32 v[88:89], v[88:89], v[232:233]
	v_exp_f32_e32 v207, v207
	v_pk_mul_f32 v[90:91], v[90:91], v[234:235]
	v_exp_f32_e32 v208, v208
	v_cvt_pk_bf16_f32 v236, v92, v93
	v_exp_f32_e32 v209, v209
	v_cvt_pk_bf16_f32 v237, v94, v95
	v_exp_f32_e32 v210, v210
	v_cvt_pk_bf16_f32 v238, v88, v89
	v_exp_f32_e32 v211, v211
	v_cvt_pk_bf16_f32 v239, v90, v91
	s_nop 0
	global_store_dwordx4 v[240:241], v[236:239], off
	v_lshl_add_u64 v[240:241], v[240:241], 0, s[100:101]
	v_pk_fma_f32 v[204:205], v[204:205], v[178:179], v[178:179] op_sel_hi:[1,0,0]
	v_pk_fma_f32 v[206:207], v[206:207], v[178:179], v[178:179] op_sel_hi:[1,0,0]
	v_pk_fma_f32 v[208:209], v[208:209], v[178:179], v[178:179] op_sel_hi:[1,0,0]
	v_pk_fma_f32 v[210:211], v[210:211], v[178:179], v[178:179] op_sel_hi:[1,0,0]
	v_rcp_f32_e32 v204, v204
	v_pk_mul_f32 v[228:229], v[60:61], v[196:197] op_sel_hi:[1,0]
	v_rcp_f32_e32 v205, v205
	v_pk_mul_f32 v[230:231], v[62:63], v[196:197] op_sel_hi:[1,0]
	v_rcp_f32_e32 v206, v206
	v_pk_mul_f32 v[232:233], v[56:57], v[196:197] op_sel_hi:[1,0]
	v_rcp_f32_e32 v207, v207
	v_pk_mul_f32 v[234:235], v[58:59], v[196:197] op_sel_hi:[1,0]
	v_rcp_f32_e32 v208, v208
	v_pk_mul_f32 v[60:61], v[60:61], v[52:53]
	v_rcp_f32_e32 v209, v209
	v_pk_mul_f32 v[62:63], v[62:63], v[54:55]
	v_rcp_f32_e32 v210, v210
	v_pk_mul_f32 v[56:57], v[56:57], v[48:49]
	v_rcp_f32_e32 v211, v211
	v_pk_mul_f32 v[58:59], v[58:59], v[50:51]
	v_exp_f32_e32 v228, v228
	v_pk_mul_f32 v[76:77], v[76:77], v[204:205]
	v_exp_f32_e32 v229, v229
	v_pk_mul_f32 v[78:79], v[78:79], v[206:207]
	v_exp_f32_e32 v230, v230
	v_pk_mul_f32 v[72:73], v[72:73], v[208:209]
	v_exp_f32_e32 v231, v231
	v_pk_mul_f32 v[74:75], v[74:75], v[210:211]
	v_exp_f32_e32 v232, v232
	v_cvt_pk_bf16_f32 v236, v76, v77
	v_exp_f32_e32 v233, v233
	v_cvt_pk_bf16_f32 v237, v78, v79
	v_exp_f32_e32 v234, v234
	v_cvt_pk_bf16_f32 v238, v72, v73
	v_exp_f32_e32 v235, v235
	v_cvt_pk_bf16_f32 v239, v74, v75
	s_nop 0
	global_store_dwordx4 v[240:241], v[236:239], off
	v_pk_fma_f32 v[228:229], v[228:229], v[180:181], v[180:181] op_sel_hi:[1,0,0]
	v_pk_fma_f32 v[230:231], v[230:231], v[180:181], v[180:181] op_sel_hi:[1,0,0]
	v_pk_fma_f32 v[232:233], v[232:233], v[180:181], v[180:181] op_sel_hi:[1,0,0]
	v_pk_fma_f32 v[234:235], v[234:235], v[180:181], v[180:181] op_sel_hi:[1,0,0]
	v_rcp_f32_e32 v228, v228
	v_pk_mul_f32 v[204:205], v[44:45], v[198:199] op_sel_hi:[1,0]
	v_rcp_f32_e32 v229, v229
	v_pk_mul_f32 v[206:207], v[46:47], v[198:199] op_sel_hi:[1,0]
	v_rcp_f32_e32 v230, v230
	v_pk_mul_f32 v[208:209], v[40:41], v[198:199] op_sel_hi:[1,0]
	v_rcp_f32_e32 v231, v231
	v_pk_mul_f32 v[210:211], v[42:43], v[198:199] op_sel_hi:[1,0]
	v_rcp_f32_e32 v232, v232
	v_pk_mul_f32 v[44:45], v[44:45], v[36:37]
	v_rcp_f32_e32 v233, v233
	v_pk_mul_f32 v[46:47], v[46:47], v[38:39]
	v_rcp_f32_e32 v234, v234
	v_pk_mul_f32 v[40:41], v[40:41], v[32:33]
	v_rcp_f32_e32 v235, v235
	v_pk_mul_f32 v[42:43], v[42:43], v[34:35]
	v_exp_f32_e32 v204, v204
	v_pk_mul_f32 v[60:61], v[60:61], v[228:229]
	v_exp_f32_e32 v205, v205
	v_pk_mul_f32 v[62:63], v[62:63], v[230:231]
	v_exp_f32_e32 v206, v206
	v_pk_mul_f32 v[56:57], v[56:57], v[232:233]
	v_exp_f32_e32 v207, v207
	v_pk_mul_f32 v[58:59], v[58:59], v[234:235]
	v_exp_f32_e32 v208, v208
	v_cvt_pk_bf16_f32 v236, v60, v61
	v_exp_f32_e32 v209, v209
	v_cvt_pk_bf16_f32 v237, v62, v63
	v_exp_f32_e32 v210, v210
	v_cvt_pk_bf16_f32 v238, v56, v57
	v_exp_f32_e32 v211, v211
	v_cvt_pk_bf16_f32 v239, v58, v59
	s_nop 0
	global_store_dwordx4 v[242:243], v[236:239], off
	v_lshl_add_u64 v[242:243], v[242:243], 0, s[100:101]
	v_pk_fma_f32 v[204:205], v[204:205], v[182:183], v[182:183] op_sel_hi:[1,0,0]
	v_pk_fma_f32 v[206:207], v[206:207], v[182:183], v[182:183] op_sel_hi:[1,0,0]
	v_pk_fma_f32 v[208:209], v[208:209], v[182:183], v[182:183] op_sel_hi:[1,0,0]
	v_pk_fma_f32 v[210:211], v[210:211], v[182:183], v[182:183] op_sel_hi:[1,0,0]
; __device__ __forceinline__ unsigned pk2(float lo, float hi) { f32x2_t v = {lo, hi}; bf16x2_t b = __builtin_convertvector(v, bf16x2_t); return __builtin_bit_cast(unsigned, b); }
; __device__ __forceinline__ float sigm(float x) { return frcp(1.f + fexp2(-LOG2E * x)); }
; #define PG8_BAR __builtin_amdgcn_s_barrier()
; template <class Epi, class Sched, bool ALIGN_EPI = false, bool SP2 = false, bool F16 = false, bool TOKPERM = false>
; __device__ __forceinline__ void gemm_phase(PG8_LAS unsigned char* lds, const Gemm g, const Sched& S, const Epi& E, int wv) {
;     ...
;         if (!has_next) break;
; #pragma unroll
;         for (int a = 0; a < 2; ++a)
; #pragma unroll
;             for (int b = 0; b < 2; ++b)
; #pragma unroll
;                 for (int m = 0; m < 4; ++m)
; #pragma unroll
;                     for (int n = 0; n < 2; ++n) acc[a][b][m][n] = (f32x4){0.f, 0.f, 0.f, 0.f};
;         cur = nxt; cA = nA; cB = nB; ++ui;
;         if constexpr (ALIGN_EPI) { if (wr == 1) PG8_BAR; }
;   __device__ __forceinline__ void operator()(const pg8::f32x4 (&acc)[2][2][4][2], const pg8::Unit& u, int wr, int wc, int fr, int fq) const {
;     ...
;       for (int m = 0; m < 4; ++m) {
;         const float r = rs[m]; float v[8];
; #pragma unroll
;         for (int n = 0; n < 2; ++n)
; #pragma unroll
;           for (int c = 0; c < 4; ++c) { const float g = acc[ai][0][m][n][c] * r, uu = acc[ai][1][m][n][c] * r; v[4 * n + c] = g * sigm(g) * uu; }
;         u32x4 w; w.x = pk2(v[0], v[1]); w.y = pk2(v[2], v[3]); w.z = pk2(v[4], v[5]); w.w = pk2(v[6], v[7]);
;         *(u32x4*)(hbuf + (unsigned)(row0 + ai * 128 + m * 16) * DFF + col0) = w;
	v_rcp_f32_e32 v204, v204
	v_pk_mul_f32 v[228:229], v[28:29], v[200:201] op_sel_hi:[1,0]
	v_rcp_f32_e32 v205, v205
	v_pk_mul_f32 v[230:231], v[30:31], v[200:201] op_sel_hi:[1,0]
	v_rcp_f32_e32 v206, v206
	v_pk_mul_f32 v[232:233], v[24:25], v[200:201] op_sel_hi:[1,0]
	v_rcp_f32_e32 v207, v207
	v_pk_mul_f32 v[234:235], v[26:27], v[200:201] op_sel_hi:[1,0]
	v_rcp_f32_e32 v208, v208
	v_pk_mul_f32 v[28:29], v[28:29], v[20:21]
	v_rcp_f32_e32 v209, v209
	v_pk_mul_f32 v[30:31], v[30:31], v[22:23]
	v_rcp_f32_e32 v210, v210
	v_pk_mul_f32 v[24:25], v[24:25], v[16:17]
	v_rcp_f32_e32 v211, v211
	v_pk_mul_f32 v[26:27], v[26:27], v[18:19]
	v_exp_f32_e32 v228, v228
	v_pk_mul_f32 v[44:45], v[44:45], v[204:205]
	v_exp_f32_e32 v229, v229
	v_pk_mul_f32 v[46:47], v[46:47], v[206:207]
	v_exp_f32_e32 v230, v230
	v_pk_mul_f32 v[40:41], v[40:41], v[208:209]
	v_exp_f32_e32 v231, v231
	v_pk_mul_f32 v[42:43], v[42:43], v[210:211]
	v_exp_f32_e32 v232, v232
	v_cvt_pk_bf16_f32 v236, v44, v45
	v_exp_f32_e32 v233, v233
	v_cvt_pk_bf16_f32 v237, v46, v47
	v_exp_f32_e32 v234, v234
	v_cvt_pk_bf16_f32 v238, v40, v41
	v_exp_f32_e32 v235, v235
	v_cvt_pk_bf16_f32 v239, v42, v43
	s_nop 0
	global_store_dwordx4 v[242:243], v[236:239], off
	v_lshl_add_u64 v[242:243], v[242:243], 0, s[100:101]
	v_pk_fma_f32 v[228:229], v[228:229], v[184:185], v[184:185] op_sel_hi:[1,0,0]
	v_pk_fma_f32 v[230:231], v[230:231], v[184:185], v[184:185] op_sel_hi:[1,0,0]
	v_pk_fma_f32 v[232:233], v[232:233], v[184:185], v[184:185] op_sel_hi:[1,0,0]
	v_pk_fma_f32 v[234:235], v[234:235], v[184:185], v[184:185] op_sel_hi:[1,0,0]
	v_rcp_f32_e32 v228, v228
	v_pk_mul_f32 v[204:205], v[12:13], v[202:203] op_sel_hi:[1,0]
	v_rcp_f32_e32 v229, v229
	v_pk_mul_f32 v[206:207], v[14:15], v[202:203] op_sel_hi:[1,0]
	v_rcp_f32_e32 v230, v230
	v_pk_mul_f32 v[208:209], v[8:9], v[202:203] op_sel_hi:[1,0]
	v_rcp_f32_e32 v231, v231
	v_pk_mul_f32 v[210:211], v[10:11], v[202:203] op_sel_hi:[1,0]
	v_rcp_f32_e32 v232, v232
	v_pk_mul_f32 v[12:13], v[12:13], v[4:5]
	v_rcp_f32_e32 v233, v233
	v_pk_mul_f32 v[14:15], v[14:15], v[6:7]
	v_rcp_f32_e32 v234, v234
	v_pk_mul_f32 v[8:9], v[8:9], v[0:1]
	v_rcp_f32_e32 v235, v235
	v_pk_mul_f32 v[10:11], v[10:11], v[2:3]
	v_exp_f32_e32 v204, v204
	v_pk_mul_f32 v[28:29], v[28:29], v[228:229]
	v_exp_f32_e32 v205, v205
	v_pk_mul_f32 v[30:31], v[30:31], v[230:231]
	v_exp_f32_e32 v206, v206
	v_pk_mul_f32 v[24:25], v[24:25], v[232:233]
	v_exp_f32_e32 v207, v207
	v_pk_mul_f32 v[26:27], v[26:27], v[234:235]
	v_exp_f32_e32 v208, v208
	v_cvt_pk_bf16_f32 v236, v28, v29
	v_exp_f32_e32 v209, v209
	v_cvt_pk_bf16_f32 v237, v30, v31
	v_exp_f32_e32 v210, v210
	v_cvt_pk_bf16_f32 v238, v24, v25
	v_exp_f32_e32 v211, v211
	v_cvt_pk_bf16_f32 v239, v26, v27
	s_nop 0
	global_store_dwordx4 v[242:243], v[236:239], off
	v_lshl_add_u64 v[242:243], v[242:243], 0, s[100:101]
	v_pk_fma_f32 v[204:205], v[204:205], v[186:187], v[186:187] op_sel_hi:[1,0,0]
	v_pk_fma_f32 v[206:207], v[206:207], v[186:187], v[186:187] op_sel_hi:[1,0,0]
	v_pk_fma_f32 v[208:209], v[208:209], v[186:187], v[186:187] op_sel_hi:[1,0,0]
	v_pk_fma_f32 v[210:211], v[210:211], v[186:187], v[186:187] op_sel_hi:[1,0,0]
	v_rcp_f32_e32 v204, v204
	v_rcp_f32_e32 v205, v205
	v_rcp_f32_e32 v206, v206
	v_rcp_f32_e32 v207, v207
	v_rcp_f32_e32 v208, v208
	v_rcp_f32_e32 v209, v209
	v_rcp_f32_e32 v210, v210
	v_rcp_f32_e32 v211, v211
	v_pk_mul_f32 v[12:13], v[12:13], v[204:205]
	v_pk_mul_f32 v[14:15], v[14:15], v[206:207]
	v_pk_mul_f32 v[8:9], v[8:9], v[208:209]
	v_pk_mul_f32 v[10:11], v[10:11], v[210:211]
	v_cvt_pk_bf16_f32 v236, v12, v13
	v_cvt_pk_bf16_f32 v237, v14, v15
	v_cvt_pk_bf16_f32 v238, v8, v9
	v_cvt_pk_bf16_f32 v239, v10, v11
	s_nop 0
	global_store_dwordx4 v[242:243], v[236:239], off
	s_andn2_b64 vcc, exec, s[4:5]
	s_mov_b64 s[4:5], -1
	s_cbranch_vccnz .LBB0_1603
	s_andn2_b64 vcc, exec, s[12:13]
	s_cbranch_vccnz .LBB0_1602
	s_barrier
	s_branch .LBB0_1602
